# diff attention: V^T fragments of a key tile read from LDS once and kept in registers for both softmax maps (8 ds_read_b128 + waits per tile removed)
# speedup vs baseline: 1.0077x; 1.0077x over previous
.LBB0_547:
	s_and_b32 s2, s9, 3
	s_mulk_i32 s2, 0x5000
	v_add_u32_e32 v75, s2, v74
	ds_read_b128 v[6:9], v75 offset:8704
	ds_read_b128 v[2:5], v75 offset:8192
	ds_read_b128 v[26:29], v75 offset:4096
	v_exp_f32_e32 v92, v92
	v_exp_f32_e32 v93, v93
	v_exp_f32_e32 v94, v94
	v_exp_f32_e32 v95, v95
	v_exp_f32_e32 v96, v96
	v_exp_f32_e32 v97, v97
	v_exp_f32_e32 v98, v98
	v_exp_f32_e32 v99, v99
	v_cvt_pk_bf16_f32 v70, v92, v93
	v_cvt_pk_bf16_f32 v71, v94, v95
	v_cvt_pk_bf16_f32 v72, v96, v97
	v_cvt_pk_bf16_f32 v73, v98, v99
	s_waitcnt lgkmcnt(1)
	s_nop 0
	v_mfma_f32_32x32x16_bf16 v[156:171], v[2:5], v[70:73], v[156:171]
	ds_read_b128 v[10:13], v75 offset:10240
	s_mov_b32 s10, s8
	s_mov_b32 s11, s8
	s_mov_b32 s9, s8
	v_exp_f32_e32 v100, v100
	v_exp_f32_e32 v101, v101
	v_exp_f32_e32 v102, v102
	v_mfma_f32_32x32x16_bf16 v[140:155], v[6:9], v[70:73], v[140:155]
	ds_read_b128 v[14:17], v75 offset:10752
	v_exp_f32_e32 v103, v103
	v_exp_f32_e32 v104, v104
	v_exp_f32_e32 v105, v105
	v_mfma_f32_16x16x32_bf16 v[214:217], v[58:61], v[70:73], v[214:217]
	v_exp_f32_e32 v106, v106
	v_exp_f32_e32 v107, v107
	v_cvt_pk_bf16_f32 v182, v100, v101
	ds_read_b128 v[22:25], v75 offset:4608
	v_cvt_pk_bf16_f32 v183, v102, v103
	v_cvt_pk_bf16_f32 v184, v104, v105
	v_cvt_pk_bf16_f32 v185, v106, v107
	s_waitcnt lgkmcnt(3)
	v_mfma_f32_32x32x16_bf16 v[34:49], v[26:29], v[178:181], 0
	s_waitcnt lgkmcnt(2)
	v_mfma_f32_32x32x16_bf16 v[156:171], v[10:13], v[182:185], v[156:171]
	ds_read_b128 v[224:227], v75 offset:12288
	v_exp_f32_e32 v76, v76
	v_exp_f32_e32 v77, v77
	v_exp_f32_e32 v78, v78
	s_waitcnt lgkmcnt(2)
	v_mfma_f32_32x32x16_bf16 v[140:155], v[14:17], v[182:185], v[140:155]
	ds_read_b128 v[228:231], v75 offset:12800
	v_exp_f32_e32 v79, v79
	v_exp_f32_e32 v80, v80
	v_exp_f32_e32 v81, v81
	v_mfma_f32_16x16x32_bf16 v[214:217], v[58:61], v[182:185], v[214:217]
	v_exp_f32_e32 v82, v82
	v_exp_f32_e32 v83, v83
	v_cvt_pk_bf16_f32 v70, v76, v77
	ds_read_b128 v[100:103], v75 offset:6144
	v_cvt_pk_bf16_f32 v71, v78, v79
	v_cvt_pk_bf16_f32 v72, v80, v81
	v_cvt_pk_bf16_f32 v73, v82, v83
	s_waitcnt lgkmcnt(3)
	v_mfma_f32_32x32x16_bf16 v[18:33], v[22:25], v[178:181], 0
	s_waitcnt lgkmcnt(2)
	v_mfma_f32_32x32x16_bf16 v[156:171], v[224:227], v[70:73], v[156:171]
	ds_read_b128 v[232:235], v75 offset:14336
	v_exp_f32_e32 v84, v84
	v_exp_f32_e32 v85, v85
	v_exp_f32_e32 v86, v86
	s_waitcnt lgkmcnt(2)
	v_mfma_f32_32x32x16_bf16 v[140:155], v[228:231], v[70:73], v[140:155]
	ds_read_b128 v[236:239], v75 offset:14848
	v_exp_f32_e32 v87, v87
	v_exp_f32_e32 v88, v88
	v_exp_f32_e32 v89, v89
	v_mfma_f32_16x16x32_bf16 v[214:217], v[58:61], v[70:73], v[214:217]
	v_exp_f32_e32 v90, v90
	v_exp_f32_e32 v91, v91
	v_cvt_pk_bf16_f32 v182, v84, v85
	ds_read_b128 v[70:73], v75 offset:6656
	v_cvt_pk_bf16_f32 v183, v86, v87
	v_cvt_pk_bf16_f32 v184, v88, v89
	v_cvt_pk_bf16_f32 v185, v90, v91
	s_waitcnt lgkmcnt(3)
	v_mfma_f32_32x32x16_bf16 v[34:49], v[100:103], v[174:177], v[34:49]
	s_waitcnt lgkmcnt(2)
	v_mfma_f32_32x32x16_bf16 v[156:171], v[232:235], v[182:185], v[156:171]
	s_waitcnt lgkmcnt(1)
	v_mfma_f32_32x32x16_bf16 v[140:155], v[236:239], v[182:185], v[140:155]
	v_mfma_f32_16x16x32_bf16 v[214:217], v[58:61], v[182:185], v[214:217]
	s_waitcnt lgkmcnt(0)
	v_mfma_f32_32x32x16_bf16 v[18:33], v[70:73], v[174:177], v[18:33]
	s_and_b32 s2, s43, 3
	s_mulk_i32 s2, 0x5000
	v_add_u32_e32 v172, s2, v74
	ds_read_b128 v[84:87], v172
	v_exp_f32_e32 v34, v34
	v_exp_f32_e32 v35, v35
	v_exp_f32_e32 v36, v36
	v_exp_f32_e32 v37, v37
	v_exp_f32_e32 v38, v38
	v_exp_f32_e32 v39, v39
	v_exp_f32_e32 v40, v40
	v_exp_f32_e32 v41, v41
	v_cvt_pk_bf16_f32 v70, v34, v35
	v_cvt_pk_bf16_f32 v71, v36, v37
	v_cvt_pk_bf16_f32 v72, v38, v39
	v_cvt_pk_bf16_f32 v73, v40, v41
	s_nop 0
	s_nop 0
	v_mfma_f32_32x32x16_bf16 v[124:139], v[2:5], v[70:73], v[124:139]
	v_exp_f32_e32 v42, v42
	v_exp_f32_e32 v43, v43
	v_exp_f32_e32 v44, v44
	s_nop 0
	v_mfma_f32_32x32x16_bf16 v[108:123], v[6:9], v[70:73], v[108:123]
	v_exp_f32_e32 v45, v45
	v_exp_f32_e32 v46, v46
	v_exp_f32_e32 v47, v47
	v_mfma_f32_16x16x32_bf16 v[214:217], v[62:65], v[70:73], v[214:217]
	v_exp_f32_e32 v48, v48
	v_exp_f32_e32 v49, v49
	v_cvt_pk_bf16_f32 v66, v42, v43
	s_waitcnt lgkmcnt(0)
	v_mfma_f32_32x32x16_bf16 v[92:107], v[84:87], v[50:53], 0
	ds_read_b128 v[88:91], v172 offset:512
	v_cvt_pk_bf16_f32 v67, v44, v45
	v_cvt_pk_bf16_f32 v68, v46, v47
	v_cvt_pk_bf16_f32 v69, v48, v49
	s_nop 0
	s_nop 0
	v_mfma_f32_32x32x16_bf16 v[124:139], v[10:13], v[66:69], v[124:139]
	v_exp_f32_e32 v18, v18
	v_exp_f32_e32 v19, v19
	v_exp_f32_e32 v20, v20
	s_nop 0
	v_mfma_f32_32x32x16_bf16 v[108:123], v[14:17], v[66:69], v[108:123]
	v_exp_f32_e32 v21, v21
	v_exp_f32_e32 v22, v22
	v_exp_f32_e32 v23, v23
	v_mfma_f32_16x16x32_bf16 v[214:217], v[62:65], v[66:69], v[214:217]
	v_exp_f32_e32 v24, v24
	v_exp_f32_e32 v25, v25
	v_cvt_pk_bf16_f32 v70, v18, v19
	s_waitcnt lgkmcnt(0)
	v_mfma_f32_32x32x16_bf16 v[76:91], v[88:91], v[50:53], 0
	ds_read_b128 v[42:45], v172 offset:2048
	v_cvt_pk_bf16_f32 v71, v20, v21
	v_cvt_pk_bf16_f32 v72, v22, v23
	v_cvt_pk_bf16_f32 v73, v24, v25
	s_nop 0
	s_nop 0
	v_mfma_f32_32x32x16_bf16 v[124:139], v[224:227], v[70:73], v[124:139]
	v_exp_f32_e32 v26, v26
	v_exp_f32_e32 v27, v27
	v_exp_f32_e32 v28, v28
	s_nop 0
	v_mfma_f32_32x32x16_bf16 v[108:123], v[228:231], v[70:73], v[108:123]
	v_exp_f32_e32 v29, v29
	v_exp_f32_e32 v30, v30
	v_exp_f32_e32 v31, v31
	v_mfma_f32_16x16x32_bf16 v[214:217], v[62:65], v[70:73], v[214:217]
	v_exp_f32_e32 v32, v32
	v_exp_f32_e32 v33, v33
	v_cvt_pk_bf16_f32 v66, v26, v27
	s_waitcnt lgkmcnt(0)
	v_mfma_f32_32x32x16_bf16 v[92:107], v[42:45], v[54:57], v[92:107]
	ds_read_b128 v[42:45], v172 offset:2560
	v_cvt_pk_bf16_f32 v67, v28, v29
	v_cvt_pk_bf16_f32 v68, v30, v31
	v_cvt_pk_bf16_f32 v69, v32, v33
	s_nop 0
	s_nop 0
	v_mfma_f32_32x32x16_bf16 v[124:139], v[232:235], v[66:69], v[124:139]
	s_nop 0
	v_mfma_f32_32x32x16_bf16 v[108:123], v[236:239], v[66:69], v[108:123]
	v_mfma_f32_16x16x32_bf16 v[214:217], v[62:65], v[66:69], v[214:217]
	s_waitcnt lgkmcnt(0)
	v_mfma_f32_32x32x16_bf16 v[76:91], v[42:45], v[54:57], v[76:91]
	s_add_i32 s2, s43, 1
	s_add_u32 s44, s44, 0x1000
	s_addc_u32 s45, s45, 0
	s_add_u32 s46, s46, 0x2000
	s_addc_u32 s47, s47, 0
	s_cmp_lg_u32 s43, s26
	s_cbranch_scc0 .LBB0_552
	s_mov_b32 s43, s2
	s_add_i32 s9, s43, -1
	s_cmp_ge_u32 s9, s28
	s_mov_b64 s[2:3], -1
	s_cbranch_scc1 .LBB0_539
	s_branch .LBB0_540
